# XCD barrier poll: the 16 counter loads issued back-to-back with one wait instead of 16 serialized load+wait steps
# baseline (speedup 1.0000x reference)
; DEVI unsigned xb_ld(unsigned* p) { return __hip_atomic_load(p, __ATOMIC_RELAXED, __HIP_MEMORY_SCOPE_AGENT); }
; DEVI void xcd_barrier_complete(unsigned* bar, unsigned x, unsigned& nloc, unsigned& nx) {
;     ...
;   for (;;) {
;     sum = 0u; cnt = 0u; mine = 0u;
; #pragma unroll
;     for (unsigned j = 0; j < 16; ++j) { const unsigned c = xb_ld(&bar[XB_XCNT(j)]); sum += c; cnt += (c > 0u) ? 1u : 0u; mine = (j == x) ? c : mine; }
;     if (sum == G) break;
;     __builtin_amdgcn_s_sleep(1);
;     if ((++sp & 255u) == 0u) { if (xb_ld(&bar[XB_TMO])) break; if (sp > XB_SPIN_CAP) { atomicAdd(&bar[XB_TMO], 1u); break; } }
;   }
.LBB0_2030:
	global_load_dword v0, v1, s[28:29] sc1
	s_mov_b64 s[10:11], -1
	s_waitcnt lgkmcnt(0)
	v_readlane_b32 s6, v249, 2
	v_readlane_b32 s7, v249, 3
	s_nop 4
	global_load_dword v2, v1, s[6:7] sc1
	v_readlane_b32 s6, v249, 4
	v_readlane_b32 s7, v249, 5
	s_nop 4
	global_load_dword v3, v1, s[6:7] sc1
	v_readlane_b32 s6, v249, 6
	v_readlane_b32 s7, v249, 7
	s_nop 4
	global_load_dword v4, v1, s[6:7] sc1
	v_readlane_b32 s6, v249, 8
	v_readlane_b32 s7, v249, 9
	s_nop 4
	global_load_dword v5, v1, s[6:7] sc1
	v_readlane_b32 s6, v249, 10
	v_readlane_b32 s7, v249, 11
	s_nop 4
	global_load_dword v6, v1, s[6:7] sc1
	v_readlane_b32 s6, v249, 12
	v_readlane_b32 s7, v249, 13
	s_nop 4
	global_load_dword v7, v1, s[6:7] sc1
	v_readlane_b32 s6, v249, 14
	v_readlane_b32 s7, v249, 15
	s_nop 4
	global_load_dword v8, v1, s[6:7] sc1
	v_readlane_b32 s6, v249, 16
	v_readlane_b32 s7, v249, 17
	s_nop 4
	global_load_dword v9, v1, s[6:7] sc1
	v_readlane_b32 s6, v249, 18
	v_readlane_b32 s7, v249, 19
	s_nop 4
	global_load_dword v10, v1, s[6:7] sc1
	v_readlane_b32 s6, v249, 20
	v_readlane_b32 s7, v249, 21
	s_nop 4
	global_load_dword v11, v1, s[6:7] sc1
	v_readlane_b32 s6, v249, 22
	v_readlane_b32 s7, v249, 23
	s_nop 4
	global_load_dword v12, v1, s[6:7] sc1
	v_readlane_b32 s6, v249, 24
	v_readlane_b32 s7, v249, 25
	s_nop 4
	global_load_dword v13, v1, s[6:7] sc1
	v_readlane_b32 s6, v249, 26
	v_readlane_b32 s7, v249, 27
	s_nop 4
	global_load_dword v14, v1, s[6:7] sc1
	v_readlane_b32 s6, v249, 28
	v_readlane_b32 s7, v249, 29
	s_nop 4
	global_load_dword v15, v1, s[6:7] sc1
	v_readlane_b32 s6, v249, 30
	v_readlane_b32 s7, v249, 31
	s_nop 4
	global_load_dword v16, v1, s[6:7] sc1
	s_mov_b64 s[6:7], -1
	s_waitcnt vmcnt(0)
	v_add_u32_e32 v17, v2, v0
	v_add_u32_e32 v17, v17, v3
	v_add_u32_e32 v17, v17, v4
	v_add_u32_e32 v17, v17, v5
	v_add_u32_e32 v17, v17, v6
	v_add_u32_e32 v17, v17, v7
	v_add_u32_e32 v17, v17, v8
	v_add_u32_e32 v17, v17, v9
	v_add_u32_e32 v17, v17, v10
	v_add_u32_e32 v17, v17, v11
	v_add_u32_e32 v17, v17, v12
	v_add_u32_e32 v17, v17, v13
	v_add_u32_e32 v17, v17, v14
	v_add_u32_e32 v17, v17, v15
	v_add_u32_e32 v17, v17, v16
	v_cmp_eq_u32_e32 vcc, s95, v17
	s_cbranch_vccnz .LBB0_2029
	s_and_b32 s6, s5, 0xff
	s_cmp_eq_u32 s6, 0
	s_mov_b64 s[6:7], -1
	s_mov_b64 s[14:15], -1
	s_sleep 1
	s_cbranch_scc0 .LBB0_2034
	v_readlane_b32 s6, v249, 0
	v_readlane_b32 s7, v249, 1
	s_nop 4
	global_load_dword v17, v1, s[6:7] sc1
	s_waitcnt vmcnt(0)
	v_cmp_eq_u32_e32 vcc, 0, v17
	s_cbranch_vccnz .LBB0_2036
	s_mov_b64 s[14:15], 0
	s_mov_b64 s[6:7], -1
